# as v79 but the second per-pair barrier (after fragment reads) moved down to just before the DMA cluster, so MFMA groups 0-2 start without waiting for all LDS reads
# baseline (speedup 1.0000x reference)
; template <int MI, bool SWAP, class Epi> ...
;     ...
;         if (kt + 1 < nk && !(prefetched && kt == 0)) { if (MI == 8) asm volatile("s_waitcnt vmcnt(6)\n\ts_barrier" ::: "memory"); else if (MI == 4) asm volatile("s_waitcnt vmcnt(4)\n\ts_barrier" ::: "memory"); else asm volatile("s_waitcnt vmcnt(3)\n\ts_barrier" ::: "memory"); }
;         else asm volatile("s_waitcnt vmcnt(0)\n\ts_barrier" ::: "memory");
;         if (kt + 2 < nk) { const int nx = (cur == 0) ? 2 : cur - 1; RING_STAGE(nx, (kt + 2) * 32); }
;         const int so = cur * STAGEB;
;         bf16x8 bf[4], af[MI];
; #pragma unroll
;         for (int j = 0; j < 4; ++j) bf[j] = *(const bf16x8*)(brdb + so + j * 1024);
; #pragma unroll
;         for (int i = 0; i < MI; ++i) af[i] = *(const bf16x8*)(ardb + so + i * 1024);
;         if (blockIdx.x & 256) __builtin_amdgcn_s_setprio(2); else __builtin_amdgcn_s_setprio(1);
.Lrp_even_inA:
	s_waitcnt vmcnt(0)
	s_barrier
	v_add_u32_e32 v140, s8, v223
	v_add_u32_e32 v144, s8, v222
	ds_read_b128 v[128:131], v140 offset:16384
	ds_read_b128 v[132:135], v140 offset:17408
	ds_read_b128 v[136:139], v140 offset:18432
	ds_read_b128 v[140:143], v140 offset:19456
	ds_read_b128 v[172:175], v144
	ds_read_b128 v[168:171], v144 offset:1024
	ds_read_b128 v[164:167], v144 offset:2048
	ds_read_b128 v[160:163], v144 offset:3072
	ds_read_b128 v[156:159], v144 offset:4096
	ds_read_b128 v[152:155], v144 offset:5120
	ds_read_b128 v[148:151], v144 offset:6144
	ds_read_b128 v[144:147], v144 offset:7168
	s_and_b64 vcc, exec, s[4:5]
	s_cbranch_vccnz .Lrp_p1_inA_e
	s_setprio 2
	s_branch .Lrp_go_inA_e

; __device__ __forceinline__ f32x4 mfma16(bf16x8 a, bf16x8 b, f32x4 c) { return __builtin_amdgcn_mfma_f32_16x16x32_bf16(a, b, c, 0, 0, 0); }
; template <int MI, bool SWAP, class Epi> ...
;     ...
;         if (blockIdx.x & 256) __builtin_amdgcn_s_setprio(2); else __builtin_amdgcn_s_setprio(1);
; #pragma unroll
;         for (int i = 0; i < MI; ++i) {
; #pragma unroll
;             for (int j = 0; j < 4; ++j) {
;                 if (SWAP) acc[i][j] = mfma16(bf[j], af[i], acc[i][j]);
;                 else acc[i][j] = mfma16(af[i], bf[j], acc[i][j]);
;             }
;         }
;         __builtin_amdgcn_s_setprio(0);
.Lrp_go_inA_e:
	s_waitcnt lgkmcnt(7)
	v_mfma_f32_16x16x32_bf16 v[124:127], v[128:131], v[172:175], v[124:127]
	v_mfma_f32_16x16x32_bf16 v[120:123], v[132:135], v[172:175], v[120:123]
	v_mfma_f32_16x16x32_bf16 v[116:119], v[136:139], v[172:175], v[116:119]
	v_mfma_f32_16x16x32_bf16 v[112:115], v[140:143], v[172:175], v[112:115]
	s_waitcnt lgkmcnt(6)
	v_mfma_f32_16x16x32_bf16 v[108:111], v[128:131], v[168:171], v[108:111]
	v_mfma_f32_16x16x32_bf16 v[104:107], v[132:135], v[168:171], v[104:107]
	v_mfma_f32_16x16x32_bf16 v[100:103], v[136:139], v[168:171], v[100:103]
	v_mfma_f32_16x16x32_bf16 v[96:99], v[140:143], v[168:171], v[96:99]
	s_waitcnt lgkmcnt(5)
	v_mfma_f32_16x16x32_bf16 v[92:95], v[128:131], v[164:167], v[92:95]
	v_mfma_f32_16x16x32_bf16 v[88:91], v[132:135], v[164:167], v[88:91]
	v_mfma_f32_16x16x32_bf16 v[84:87], v[136:139], v[164:167], v[84:87]
	v_mfma_f32_16x16x32_bf16 v[80:83], v[140:143], v[164:167], v[80:83]
	s_waitcnt lgkmcnt(0)
	s_barrier
	s_sub_i32 vcc_lo, s8, s9
	v_lshl_add_u64 v[172:173], v[178:179], 0, s[6:7]
	s_add_i32 s29, s9, s11
	s_mov_b32 m0, s29
	v_lshl_add_u64 v[168:169], v[172:173], 0, 64
	global_load_lds_dwordx4 v[172:173], off
	s_add_i32 m0, s29, vcc_lo
	s_nop 0
	global_load_lds_dwordx4 v[168:169], off
	s_mov_b64 s[38:39], 0x8000
	v_lshl_add_u64 v[174:175], v[172:173], 0, s[38:39]
	s_add_i32 s30, s29, 0x400
	s_mov_b32 m0, s30
	v_lshl_add_u64 v[168:169], v[174:175], 0, 64
	global_load_lds_dwordx4 v[174:175], off
	s_add_i32 m0, s30, vcc_lo
	s_nop 0
	global_load_lds_dwordx4 v[168:169], off
	s_mov_b64 s[30:31], 0x10000
	v_lshl_add_u64 v[174:175], v[172:173], 0, s[30:31]
	s_add_i32 s30, s29, 0x800
	s_mov_b32 m0, s30
	v_lshl_add_u64 v[168:169], v[174:175], 0, 64
	global_load_lds_dwordx4 v[174:175], off
	s_add_i32 m0, s30, vcc_lo
	s_nop 0
	global_load_lds_dwordx4 v[168:169], off
	s_mov_b64 s[30:31], 0x18000
	v_lshl_add_u64 v[172:173], v[172:173], 0, s[30:31]
	s_addk_i32 s29, 0xc00
	s_mov_b32 m0, s29
	v_lshl_add_u64 v[168:169], v[172:173], 0, 64
	global_load_lds_dwordx4 v[172:173], off
	s_add_i32 m0, s29, vcc_lo
	s_nop 0
	global_load_lds_dwordx4 v[168:169], off
	v_lshl_add_u64 v[172:173], v[176:177], 0, s[6:7]
	s_add_i32 s9, s9, s22
	s_mov_b32 m0, s9
	v_lshl_add_u64 v[168:169], v[172:173], 0, 64
	global_load_lds_dwordx4 v[172:173], off
	s_add_i32 m0, s9, vcc_lo
	s_nop 0
	global_load_lds_dwordx4 v[168:169], off
	v_lshl_add_u64 v[172:173], v[172:173], 0, s[38:39]
	s_addk_i32 s9, 0x400
	s_mov_b32 m0, s9
	v_lshl_add_u64 v[168:169], v[172:173], 0, 64
	global_load_lds_dwordx4 v[172:173], off
	s_add_i32 m0, s9, vcc_lo
	s_nop 0
	global_load_lds_dwordx4 v[168:169], off
	v_mfma_f32_16x16x32_bf16 v[76:79], v[128:131], v[160:163], v[76:79]
	v_mfma_f32_16x16x32_bf16 v[72:75], v[132:135], v[160:163], v[72:75]
	v_mfma_f32_16x16x32_bf16 v[68:71], v[136:139], v[160:163], v[68:71]
	v_mfma_f32_16x16x32_bf16 v[64:67], v[140:143], v[160:163], v[64:67]
	v_mfma_f32_16x16x32_bf16 v[60:63], v[128:131], v[156:159], v[60:63]
	v_mfma_f32_16x16x32_bf16 v[56:59], v[132:135], v[156:159], v[56:59]
	v_mfma_f32_16x16x32_bf16 v[52:55], v[136:139], v[156:159], v[52:55]
	v_mfma_f32_16x16x32_bf16 v[48:51], v[140:143], v[156:159], v[48:51]
	v_mfma_f32_16x16x32_bf16 v[44:47], v[128:131], v[152:155], v[44:47]
	v_mfma_f32_16x16x32_bf16 v[40:43], v[132:135], v[152:155], v[40:43]
	v_mfma_f32_16x16x32_bf16 v[36:39], v[136:139], v[152:155], v[36:39]
	v_mfma_f32_16x16x32_bf16 v[32:35], v[140:143], v[152:155], v[32:35]
	v_mfma_f32_16x16x32_bf16 v[28:31], v[128:131], v[148:151], v[28:31]
	v_mfma_f32_16x16x32_bf16 v[24:27], v[132:135], v[148:151], v[24:27]
	v_mfma_f32_16x16x32_bf16 v[20:23], v[136:139], v[148:151], v[20:23]
	v_mfma_f32_16x16x32_bf16 v[16:19], v[140:143], v[148:151], v[16:19]
	v_mfma_f32_16x16x32_bf16 v[12:15], v[128:131], v[144:147], v[12:15]
	v_mfma_f32_16x16x32_bf16 v[8:11], v[132:135], v[144:147], v[8:11]
	v_mfma_f32_16x16x32_bf16 v[4:7], v[136:139], v[144:147], v[4:7]
	v_mfma_f32_16x16x32_bf16 v[0:3], v[140:143], v[144:147], v[0:3]

; template <int MI, bool SWAP, class Epi> ...
;     ...
;         if (kt + 1 < nk && !(prefetched && kt == 0)) { if (MI == 8) asm volatile("s_waitcnt vmcnt(6)\n\ts_barrier" ::: "memory"); else if (MI == 4) asm volatile("s_waitcnt vmcnt(4)\n\ts_barrier" ::: "memory"); else asm volatile("s_waitcnt vmcnt(3)\n\ts_barrier" ::: "memory"); }
;         else asm volatile("s_waitcnt vmcnt(0)\n\ts_barrier" ::: "memory");
;         if (kt + 2 < nk) { const int nx = (cur == 0) ? 2 : cur - 1; RING_STAGE(nx, (kt + 2) * 32); }
;         const int so = cur * STAGEB;
;         bf16x8 bf[4], af[MI];
; #pragma unroll
;         for (int j = 0; j < 4; ++j) bf[j] = *(const bf16x8*)(brdb + so + j * 1024);
; #pragma unroll
;         for (int i = 0; i < MI; ++i) af[i] = *(const bf16x8*)(ardb + so + i * 1024);
;         if (blockIdx.x & 256) __builtin_amdgcn_s_setprio(2); else __builtin_amdgcn_s_setprio(1);
.Lrp_even_inB:
	s_waitcnt vmcnt(0)
	s_barrier
	v_add_u32_e32 v140, s6, v223
	v_add_u32_e32 v144, s6, v222
	ds_read_b128 v[128:131], v140 offset:16384
	ds_read_b128 v[132:135], v140 offset:17408
	ds_read_b128 v[136:139], v140 offset:18432
	ds_read_b128 v[140:143], v140 offset:19456
	ds_read_b128 v[172:175], v144
	ds_read_b128 v[168:171], v144 offset:1024
	ds_read_b128 v[164:167], v144 offset:2048
	ds_read_b128 v[160:163], v144 offset:3072
	ds_read_b128 v[156:159], v144 offset:4096
	ds_read_b128 v[152:155], v144 offset:5120
	ds_read_b128 v[148:151], v144 offset:6144
	ds_read_b128 v[144:147], v144 offset:7168
	s_and_b64 vcc, exec, s[0:1]
	s_cbranch_vccnz .Lrp_p1_inB_e
	s_setprio 2
	s_branch .Lrp_go_inB_e

; __device__ __forceinline__ f32x4 mfma16(bf16x8 a, bf16x8 b, f32x4 c) { return __builtin_amdgcn_mfma_f32_16x16x32_bf16(a, b, c, 0, 0, 0); }
; template <int MI, bool SWAP, class Epi> ...
;     ...
;         if (blockIdx.x & 256) __builtin_amdgcn_s_setprio(2); else __builtin_amdgcn_s_setprio(1);
; #pragma unroll
;         for (int i = 0; i < MI; ++i) {
; #pragma unroll
;             for (int j = 0; j < 4; ++j) {
;                 if (SWAP) acc[i][j] = mfma16(bf[j], af[i], acc[i][j]);
;                 else acc[i][j] = mfma16(af[i], bf[j], acc[i][j]);
;             }
;         }
;         __builtin_amdgcn_s_setprio(0);
.Lrp_go_inB_e:
	s_waitcnt lgkmcnt(7)
	v_mfma_f32_16x16x32_bf16 v[124:127], v[172:175], v[128:131], v[124:127]
	v_mfma_f32_16x16x32_bf16 v[120:123], v[172:175], v[132:135], v[120:123]
	v_mfma_f32_16x16x32_bf16 v[116:119], v[172:175], v[136:139], v[116:119]
	v_mfma_f32_16x16x32_bf16 v[112:115], v[172:175], v[140:143], v[112:115]
	s_waitcnt lgkmcnt(6)
	v_mfma_f32_16x16x32_bf16 v[108:111], v[168:171], v[128:131], v[108:111]
	v_mfma_f32_16x16x32_bf16 v[104:107], v[168:171], v[132:135], v[104:107]
	v_mfma_f32_16x16x32_bf16 v[100:103], v[168:171], v[136:139], v[100:103]
	v_mfma_f32_16x16x32_bf16 v[96:99], v[168:171], v[140:143], v[96:99]
	s_waitcnt lgkmcnt(5)
	v_mfma_f32_16x16x32_bf16 v[92:95], v[164:167], v[128:131], v[92:95]
	v_mfma_f32_16x16x32_bf16 v[88:91], v[164:167], v[132:135], v[88:91]
	v_mfma_f32_16x16x32_bf16 v[84:87], v[164:167], v[136:139], v[84:87]
	v_mfma_f32_16x16x32_bf16 v[80:83], v[164:167], v[140:143], v[80:83]
	s_waitcnt lgkmcnt(0)
	s_barrier
	s_sub_i32 vcc_lo, s6, s7
	v_lshl_add_u64 v[172:173], v[178:179], 0, s[4:5]
	s_add_i32 s23, s7, s9
	s_mov_b32 m0, s23
	v_lshl_add_u64 v[168:169], v[172:173], 0, 64
	global_load_lds_dwordx4 v[172:173], off
	s_add_i32 m0, s23, vcc_lo
	s_nop 0
	global_load_lds_dwordx4 v[168:169], off
	s_mov_b64 s[30:31], 0x8000
	v_lshl_add_u64 v[174:175], v[172:173], 0, s[30:31]
	s_add_i32 s24, s23, 0x400
	s_mov_b32 m0, s24
	v_lshl_add_u64 v[168:169], v[174:175], 0, 64
	global_load_lds_dwordx4 v[174:175], off
	s_add_i32 m0, s24, vcc_lo
	s_nop 0
	global_load_lds_dwordx4 v[168:169], off
	s_mov_b64 s[24:25], 0x10000
	v_lshl_add_u64 v[174:175], v[172:173], 0, s[24:25]
	s_add_i32 s24, s23, 0x800
	s_mov_b32 m0, s24
	v_lshl_add_u64 v[168:169], v[174:175], 0, 64
	global_load_lds_dwordx4 v[174:175], off
	s_add_i32 m0, s24, vcc_lo
	s_nop 0
	global_load_lds_dwordx4 v[168:169], off
	s_mov_b64 s[24:25], 0x18000
	v_lshl_add_u64 v[172:173], v[172:173], 0, s[24:25]
	s_addk_i32 s23, 0xc00
	s_mov_b32 m0, s23
	v_lshl_add_u64 v[168:169], v[172:173], 0, 64
	global_load_lds_dwordx4 v[172:173], off
	s_add_i32 m0, s23, vcc_lo
	s_nop 0
	global_load_lds_dwordx4 v[168:169], off
	v_lshl_add_u64 v[172:173], v[176:177], 0, s[4:5]
	s_add_i32 s7, s7, s10
	s_mov_b32 m0, s7
	v_lshl_add_u64 v[168:169], v[172:173], 0, 64
	global_load_lds_dwordx4 v[172:173], off
	s_add_i32 m0, s7, vcc_lo
	s_nop 0
	global_load_lds_dwordx4 v[168:169], off
	v_lshl_add_u64 v[172:173], v[172:173], 0, s[30:31]
	s_addk_i32 s7, 0x400
	s_mov_b32 m0, s7
	v_lshl_add_u64 v[168:169], v[172:173], 0, 64
	global_load_lds_dwordx4 v[172:173], off
	s_add_i32 m0, s7, vcc_lo
	s_nop 0
	global_load_lds_dwordx4 v[168:169], off
	v_mfma_f32_16x16x32_bf16 v[76:79], v[160:163], v[128:131], v[76:79]
	v_mfma_f32_16x16x32_bf16 v[72:75], v[160:163], v[132:135], v[72:75]
	v_mfma_f32_16x16x32_bf16 v[68:71], v[160:163], v[136:139], v[68:71]
	v_mfma_f32_16x16x32_bf16 v[64:67], v[160:163], v[140:143], v[64:67]
	v_mfma_f32_16x16x32_bf16 v[60:63], v[156:159], v[128:131], v[60:63]
	v_mfma_f32_16x16x32_bf16 v[56:59], v[156:159], v[132:135], v[56:59]
	v_mfma_f32_16x16x32_bf16 v[52:55], v[156:159], v[136:139], v[52:55]
	v_mfma_f32_16x16x32_bf16 v[48:51], v[156:159], v[140:143], v[48:51]
	v_mfma_f32_16x16x32_bf16 v[44:47], v[152:155], v[128:131], v[44:47]
	v_mfma_f32_16x16x32_bf16 v[40:43], v[152:155], v[132:135], v[40:43]
	v_mfma_f32_16x16x32_bf16 v[36:39], v[152:155], v[136:139], v[36:39]
	v_mfma_f32_16x16x32_bf16 v[32:35], v[152:155], v[140:143], v[32:35]
	v_mfma_f32_16x16x32_bf16 v[28:31], v[148:151], v[128:131], v[28:31]
	v_mfma_f32_16x16x32_bf16 v[24:27], v[148:151], v[132:135], v[24:27]
	v_mfma_f32_16x16x32_bf16 v[20:23], v[148:151], v[136:139], v[20:23]
	v_mfma_f32_16x16x32_bf16 v[16:19], v[148:151], v[140:143], v[16:19]
	v_mfma_f32_16x16x32_bf16 v[12:15], v[144:147], v[128:131], v[12:15]
	v_mfma_f32_16x16x32_bf16 v[8:11], v[144:147], v[132:135], v[8:11]
	v_mfma_f32_16x16x32_bf16 v[4:7], v[144:147], v[136:139], v[4:7]
	v_mfma_f32_16x16x32_bf16 v[0:3], v[144:147], v[140:143], v[0:3]

; template <int MI, bool SWAP, class Epi> ...
;     ...
;         if (kt + 1 < nk && !(prefetched && kt == 0)) { if (MI == 8) asm volatile("s_waitcnt vmcnt(6)\n\ts_barrier" ::: "memory"); else if (MI == 4) asm volatile("s_waitcnt vmcnt(4)\n\ts_barrier" ::: "memory"); else asm volatile("s_waitcnt vmcnt(3)\n\ts_barrier" ::: "memory"); }
;         else asm volatile("s_waitcnt vmcnt(0)\n\ts_barrier" ::: "memory");
;         if (kt + 2 < nk) { const int nx = (cur == 0) ? 2 : cur - 1; RING_STAGE(nx, (kt + 2) * 32); }
;         const int so = cur * STAGEB;
;         bf16x8 bf[4], af[MI];
; #pragma unroll
;         for (int j = 0; j < 4; ++j) bf[j] = *(const bf16x8*)(brdb + so + j * 1024);
; #pragma unroll
;         for (int i = 0; i < MI; ++i) af[i] = *(const bf16x8*)(ardb + so + i * 1024);
;         if (blockIdx.x & 256) __builtin_amdgcn_s_setprio(2); else __builtin_amdgcn_s_setprio(1);
.Lrp_even_outp:
	s_waitcnt vmcnt(0)
	s_barrier
	v_add_u32_e32 v140, s8, v223
	v_add_u32_e32 v144, s8, v222
	ds_read_b128 v[128:131], v140 offset:16384
	ds_read_b128 v[132:135], v140 offset:17408
	ds_read_b128 v[136:139], v140 offset:18432
	ds_read_b128 v[140:143], v140 offset:19456
	ds_read_b128 v[172:175], v144
	ds_read_b128 v[168:171], v144 offset:1024
	ds_read_b128 v[164:167], v144 offset:2048
	ds_read_b128 v[160:163], v144 offset:3072
	ds_read_b128 v[156:159], v144 offset:4096
	ds_read_b128 v[152:155], v144 offset:5120
	ds_read_b128 v[148:151], v144 offset:6144
	ds_read_b128 v[144:147], v144 offset:7168
	s_and_b64 vcc, exec, s[0:1]
	s_cbranch_vccnz .Lrp_p1_outp_e
	s_setprio 2
	s_branch .Lrp_go_outp_e

; __device__ __forceinline__ f32x4 mfma16(bf16x8 a, bf16x8 b, f32x4 c) { return __builtin_amdgcn_mfma_f32_16x16x32_bf16(a, b, c, 0, 0, 0); }
; template <int MI, bool SWAP, class Epi> ...
;     ...
;         if (blockIdx.x & 256) __builtin_amdgcn_s_setprio(2); else __builtin_amdgcn_s_setprio(1);
; #pragma unroll
;         for (int i = 0; i < MI; ++i) {
; #pragma unroll
;             for (int j = 0; j < 4; ++j) {
;                 if (SWAP) acc[i][j] = mfma16(bf[j], af[i], acc[i][j]);
;                 else acc[i][j] = mfma16(af[i], bf[j], acc[i][j]);
;             }
;         }
;         __builtin_amdgcn_s_setprio(0);
.Lrp_go_outp_e:
	s_waitcnt lgkmcnt(7)
	v_mfma_f32_16x16x32_bf16 v[120:123], v[128:131], v[172:175], v[120:123]
	v_mfma_f32_16x16x32_bf16 v[116:119], v[132:135], v[172:175], v[116:119]
	v_mfma_f32_16x16x32_bf16 v[112:115], v[136:139], v[172:175], v[112:115]
	v_mfma_f32_16x16x32_bf16 v[108:111], v[140:143], v[172:175], v[108:111]
	s_waitcnt lgkmcnt(6)
	v_mfma_f32_16x16x32_bf16 v[104:107], v[128:131], v[168:171], v[104:107]
	v_mfma_f32_16x16x32_bf16 v[100:103], v[132:135], v[168:171], v[100:103]
	v_mfma_f32_16x16x32_bf16 v[96:99], v[136:139], v[168:171], v[96:99]
	v_mfma_f32_16x16x32_bf16 v[92:95], v[140:143], v[168:171], v[92:95]
	s_waitcnt lgkmcnt(5)
	v_mfma_f32_16x16x32_bf16 v[88:91], v[128:131], v[164:167], v[88:91]
	v_mfma_f32_16x16x32_bf16 v[84:87], v[132:135], v[164:167], v[84:87]
	v_mfma_f32_16x16x32_bf16 v[80:83], v[136:139], v[164:167], v[80:83]
	v_mfma_f32_16x16x32_bf16 v[76:79], v[140:143], v[164:167], v[76:79]
	s_waitcnt lgkmcnt(0)
	s_barrier
	s_sub_i32 vcc_lo, s8, s9
	v_lshl_add_u64 v[172:173], v[178:179], 0, s[6:7]
	s_add_i32 s29, s9, s24
	s_mov_b32 m0, s29
	v_lshl_add_u64 v[168:169], v[172:173], 0, 64
	global_load_lds_dwordx4 v[172:173], off
	s_add_i32 m0, s29, vcc_lo
	s_nop 0
	global_load_lds_dwordx4 v[168:169], off
	s_mov_b64 s[34:35], 0x8000
	v_lshl_add_u64 v[174:175], v[172:173], 0, s[34:35]
	s_add_i32 s30, s29, 0x400
	s_mov_b32 m0, s30
	v_lshl_add_u64 v[168:169], v[174:175], 0, 64
	global_load_lds_dwordx4 v[174:175], off
	s_add_i32 m0, s30, vcc_lo
	s_nop 0
	global_load_lds_dwordx4 v[168:169], off
	s_mov_b64 s[30:31], 0x10000
	v_lshl_add_u64 v[174:175], v[172:173], 0, s[30:31]
	s_add_i32 s30, s29, 0x800
	s_mov_b32 m0, s30
	v_lshl_add_u64 v[168:169], v[174:175], 0, 64
	global_load_lds_dwordx4 v[174:175], off
	s_add_i32 m0, s30, vcc_lo
	s_nop 0
	global_load_lds_dwordx4 v[168:169], off
	s_mov_b64 s[30:31], 0x18000
	v_lshl_add_u64 v[172:173], v[172:173], 0, s[30:31]
	s_addk_i32 s29, 0xc00
	s_mov_b32 m0, s29
	v_lshl_add_u64 v[168:169], v[172:173], 0, 64
	global_load_lds_dwordx4 v[172:173], off
	s_add_i32 m0, s29, vcc_lo
	s_nop 0
	global_load_lds_dwordx4 v[168:169], off
	v_lshl_add_u64 v[172:173], v[176:177], 0, s[6:7]
	s_add_i32 s9, s9, s25
	s_mov_b32 m0, s9
	v_lshl_add_u64 v[168:169], v[172:173], 0, 64
	global_load_lds_dwordx4 v[172:173], off
	s_add_i32 m0, s9, vcc_lo
	s_nop 0
	global_load_lds_dwordx4 v[168:169], off
	v_lshl_add_u64 v[172:173], v[172:173], 0, s[34:35]
	s_addk_i32 s9, 0x400
	s_mov_b32 m0, s9
	v_lshl_add_u64 v[168:169], v[172:173], 0, 64
	global_load_lds_dwordx4 v[172:173], off
	s_add_i32 m0, s9, vcc_lo
	s_nop 0
	global_load_lds_dwordx4 v[168:169], off
	v_mfma_f32_16x16x32_bf16 v[72:75], v[128:131], v[160:163], v[72:75]
	v_mfma_f32_16x16x32_bf16 v[68:71], v[132:135], v[160:163], v[68:71]
	v_mfma_f32_16x16x32_bf16 v[64:67], v[136:139], v[160:163], v[64:67]
	v_mfma_f32_16x16x32_bf16 v[60:63], v[140:143], v[160:163], v[60:63]
	v_mfma_f32_16x16x32_bf16 v[56:59], v[128:131], v[156:159], v[56:59]
	v_mfma_f32_16x16x32_bf16 v[52:55], v[132:135], v[156:159], v[52:55]
	v_mfma_f32_16x16x32_bf16 v[48:51], v[136:139], v[156:159], v[48:51]
	v_mfma_f32_16x16x32_bf16 v[44:47], v[140:143], v[156:159], v[44:47]
	v_mfma_f32_16x16x32_bf16 v[40:43], v[128:131], v[152:155], v[40:43]
	v_mfma_f32_16x16x32_bf16 v[36:39], v[132:135], v[152:155], v[36:39]
	v_mfma_f32_16x16x32_bf16 v[32:35], v[136:139], v[152:155], v[32:35]
	v_mfma_f32_16x16x32_bf16 v[28:31], v[140:143], v[152:155], v[28:31]
	v_mfma_f32_16x16x32_bf16 v[24:27], v[128:131], v[148:151], v[24:27]
	v_mfma_f32_16x16x32_bf16 v[20:23], v[132:135], v[148:151], v[20:23]
	v_mfma_f32_16x16x32_bf16 v[16:19], v[136:139], v[148:151], v[16:19]
	v_mfma_f32_16x16x32_bf16 v[12:15], v[140:143], v[148:151], v[12:15]
	v_mfma_f32_16x16x32_bf16 v[8:11], v[128:131], v[144:147], v[8:11]
	v_mfma_f32_16x16x32_bf16 v[4:7], v[132:135], v[144:147], v[4:7]
	v_mfma_f32_16x16x32_bf16 v[0:3], v[136:139], v[144:147], v[0:3]
	v_mfma_f32_16x16x32_bf16 v[124:127], v[140:143], v[144:147], v[124:127]

; __device__ __forceinline__ f32x4 mfma16(bf16x8 a, bf16x8 b, f32x4 c) { return __builtin_amdgcn_mfma_f32_16x16x32_bf16(a, b, c, 0, 0, 0); }
; template <int MI, bool SWAP, class Epi> ...
;     ...
;         if (blockIdx.x & 256) __builtin_amdgcn_s_setprio(2); else __builtin_amdgcn_s_setprio(1);
; #pragma unroll
;         for (int i = 0; i < MI; ++i) {
; #pragma unroll
;             for (int j = 0; j < 4; ++j) {
;                 if (SWAP) acc[i][j] = mfma16(bf[j], af[i], acc[i][j]);
;                 else acc[i][j] = mfma16(af[i], bf[j], acc[i][j]);
;             }
;         }
;         __builtin_amdgcn_s_setprio(0);
.Lrp_go_ff1_e:
	s_waitcnt lgkmcnt(7)
	v_mfma_f32_16x16x32_bf16 v[120:123], v[128:131], v[172:175], v[120:123]
	v_mfma_f32_16x16x32_bf16 v[116:119], v[132:135], v[172:175], v[116:119]
	v_mfma_f32_16x16x32_bf16 v[112:115], v[136:139], v[172:175], v[112:115]
	v_mfma_f32_16x16x32_bf16 v[108:111], v[140:143], v[172:175], v[108:111]
	s_waitcnt lgkmcnt(6)
	v_mfma_f32_16x16x32_bf16 v[104:107], v[128:131], v[168:171], v[104:107]
	v_mfma_f32_16x16x32_bf16 v[100:103], v[132:135], v[168:171], v[100:103]
	v_mfma_f32_16x16x32_bf16 v[96:99], v[136:139], v[168:171], v[96:99]
	v_mfma_f32_16x16x32_bf16 v[92:95], v[140:143], v[168:171], v[92:95]
	s_waitcnt lgkmcnt(5)
	v_mfma_f32_16x16x32_bf16 v[88:91], v[128:131], v[164:167], v[88:91]
	v_mfma_f32_16x16x32_bf16 v[84:87], v[132:135], v[164:167], v[84:87]
	v_mfma_f32_16x16x32_bf16 v[80:83], v[136:139], v[164:167], v[80:83]
	v_mfma_f32_16x16x32_bf16 v[76:79], v[140:143], v[164:167], v[76:79]
	s_waitcnt lgkmcnt(0)
	s_barrier
	s_sub_i32 vcc_lo, s8, s9
	v_lshl_add_u64 v[172:173], v[178:179], 0, s[6:7]
	s_add_i32 s28, s9, s23
	s_mov_b32 m0, s28
	v_lshl_add_u64 v[168:169], v[172:173], 0, 64
	global_load_lds_dwordx4 v[172:173], off
	s_add_i32 m0, s28, vcc_lo
	s_nop 0
	global_load_lds_dwordx4 v[168:169], off
	s_mov_b64 s[12:13], 0x8000
	v_lshl_add_u64 v[174:175], v[172:173], 0, s[12:13]
	s_add_i32 s29, s28, 0x400
	s_mov_b32 m0, s29
	v_lshl_add_u64 v[168:169], v[174:175], 0, 64
	global_load_lds_dwordx4 v[174:175], off
	s_add_i32 m0, s29, vcc_lo
	s_nop 0
	global_load_lds_dwordx4 v[168:169], off
	s_mov_b64 s[14:15], 0x10000
	v_lshl_add_u64 v[174:175], v[172:173], 0, s[14:15]
	s_add_i32 s29, s28, 0x800
	s_mov_b32 m0, s29
	v_lshl_add_u64 v[168:169], v[174:175], 0, 64
	global_load_lds_dwordx4 v[174:175], off
	s_add_i32 m0, s29, vcc_lo
	s_nop 0
	global_load_lds_dwordx4 v[168:169], off
	s_mov_b64 s[14:15], 0x18000
	v_lshl_add_u64 v[172:173], v[172:173], 0, s[14:15]
	s_addk_i32 s28, 0xc00
	s_mov_b32 m0, s28
	v_lshl_add_u64 v[168:169], v[172:173], 0, 64
	global_load_lds_dwordx4 v[172:173], off
	s_add_i32 m0, s28, vcc_lo
	s_nop 0
	global_load_lds_dwordx4 v[168:169], off
	v_lshl_add_u64 v[172:173], v[176:177], 0, s[6:7]
	s_add_i32 s9, s9, s24
	s_mov_b32 m0, s9
	v_lshl_add_u64 v[168:169], v[172:173], 0, 64
	global_load_lds_dwordx4 v[172:173], off
	s_add_i32 m0, s9, vcc_lo
	s_nop 0
	global_load_lds_dwordx4 v[168:169], off
	v_lshl_add_u64 v[172:173], v[172:173], 0, s[12:13]
	s_addk_i32 s9, 0x400
	s_mov_b32 m0, s9
	v_lshl_add_u64 v[168:169], v[172:173], 0, 64
	global_load_lds_dwordx4 v[172:173], off
	s_add_i32 m0, s9, vcc_lo
	s_nop 0
	global_load_lds_dwordx4 v[168:169], off
	v_mfma_f32_16x16x32_bf16 v[72:75], v[128:131], v[160:163], v[72:75]
	v_mfma_f32_16x16x32_bf16 v[68:71], v[132:135], v[160:163], v[68:71]
	v_mfma_f32_16x16x32_bf16 v[64:67], v[136:139], v[160:163], v[64:67]
	v_mfma_f32_16x16x32_bf16 v[60:63], v[140:143], v[160:163], v[60:63]
	v_mfma_f32_16x16x32_bf16 v[56:59], v[128:131], v[156:159], v[56:59]
	v_mfma_f32_16x16x32_bf16 v[52:55], v[132:135], v[156:159], v[52:55]
	v_mfma_f32_16x16x32_bf16 v[48:51], v[136:139], v[156:159], v[48:51]
	v_mfma_f32_16x16x32_bf16 v[44:47], v[140:143], v[156:159], v[44:47]
	v_mfma_f32_16x16x32_bf16 v[40:43], v[128:131], v[152:155], v[40:43]
	v_mfma_f32_16x16x32_bf16 v[36:39], v[132:135], v[152:155], v[36:39]
	v_mfma_f32_16x16x32_bf16 v[32:35], v[136:139], v[152:155], v[32:35]
	v_mfma_f32_16x16x32_bf16 v[28:31], v[140:143], v[152:155], v[28:31]
	v_mfma_f32_16x16x32_bf16 v[24:27], v[128:131], v[148:151], v[24:27]
	v_mfma_f32_16x16x32_bf16 v[20:23], v[132:135], v[148:151], v[20:23]
	v_mfma_f32_16x16x32_bf16 v[16:19], v[136:139], v[148:151], v[16:19]
	v_mfma_f32_16x16x32_bf16 v[12:15], v[140:143], v[148:151], v[12:15]
	v_mfma_f32_16x16x32_bf16 v[8:11], v[128:131], v[144:147], v[8:11]
	v_mfma_f32_16x16x32_bf16 v[4:7], v[132:135], v[144:147], v[4:7]
	v_mfma_f32_16x16x32_bf16 v[0:3], v[136:139], v[144:147], v[0:3]
	v_mfma_f32_16x16x32_bf16 v[124:127], v[140:143], v[144:147], v[124:127]

; __device__ __forceinline__ f32x4 mfma16(bf16x8 a, bf16x8 b, f32x4 c) { return __builtin_amdgcn_mfma_f32_16x16x32_bf16(a, b, c, 0, 0, 0); }
; template <int MI, bool SWAP, class Epi> ...
;     ...
;         if (blockIdx.x & 256) __builtin_amdgcn_s_setprio(2); else __builtin_amdgcn_s_setprio(1);
; #pragma unroll
;         for (int i = 0; i < MI; ++i) {
; #pragma unroll
;             for (int j = 0; j < 4; ++j) {
;                 if (SWAP) acc[i][j] = mfma16(bf[j], af[i], acc[i][j]);
;                 else acc[i][j] = mfma16(af[i], bf[j], acc[i][j]);
;             }
;         }
;         __builtin_amdgcn_s_setprio(0);
.Lrp_go_ff2_e:
	s_waitcnt lgkmcnt(7)
	v_mfma_f32_16x16x32_bf16 v[120:123], v[128:131], v[172:175], v[120:123]
	v_mfma_f32_16x16x32_bf16 v[116:119], v[132:135], v[172:175], v[116:119]
	v_mfma_f32_16x16x32_bf16 v[112:115], v[136:139], v[172:175], v[112:115]
	v_mfma_f32_16x16x32_bf16 v[108:111], v[140:143], v[172:175], v[108:111]
	s_waitcnt lgkmcnt(6)
	v_mfma_f32_16x16x32_bf16 v[104:107], v[128:131], v[168:171], v[104:107]
	v_mfma_f32_16x16x32_bf16 v[100:103], v[132:135], v[168:171], v[100:103]
	v_mfma_f32_16x16x32_bf16 v[96:99], v[136:139], v[168:171], v[96:99]
	v_mfma_f32_16x16x32_bf16 v[92:95], v[140:143], v[168:171], v[92:95]
	s_waitcnt lgkmcnt(5)
	v_mfma_f32_16x16x32_bf16 v[88:91], v[128:131], v[164:167], v[88:91]
	v_mfma_f32_16x16x32_bf16 v[84:87], v[132:135], v[164:167], v[84:87]
	v_mfma_f32_16x16x32_bf16 v[80:83], v[136:139], v[164:167], v[80:83]
	v_mfma_f32_16x16x32_bf16 v[76:79], v[140:143], v[164:167], v[76:79]
	s_waitcnt lgkmcnt(0)
	s_barrier
	s_sub_i32 vcc_lo, s8, s9
	v_lshl_add_u64 v[172:173], v[178:179], 0, s[6:7]
	s_add_i32 s31, s9, s26
	s_mov_b32 m0, s31
	v_lshl_add_u64 v[168:169], v[172:173], 0, 64
	global_load_lds_dwordx4 v[172:173], off
	s_add_i32 m0, s31, vcc_lo
	s_nop 0
	global_load_lds_dwordx4 v[168:169], off
	s_mov_b64 s[12:13], 0x20000
	v_lshl_add_u64 v[174:175], v[172:173], 0, s[12:13]
	s_add_i32 s34, s31, 0x400
	s_mov_b32 m0, s34
	v_lshl_add_u64 v[168:169], v[174:175], 0, 64
	global_load_lds_dwordx4 v[174:175], off
	s_add_i32 m0, s34, vcc_lo
	s_nop 0
	global_load_lds_dwordx4 v[168:169], off
	s_mov_b64 s[34:35], 0x40000
	v_lshl_add_u64 v[174:175], v[172:173], 0, s[34:35]
	s_add_i32 s34, s31, 0x800
	s_mov_b32 m0, s34
	v_lshl_add_u64 v[168:169], v[174:175], 0, 64
	global_load_lds_dwordx4 v[174:175], off
	s_add_i32 m0, s34, vcc_lo
	s_nop 0
	global_load_lds_dwordx4 v[168:169], off
	s_mov_b64 s[34:35], 0x60000
	v_lshl_add_u64 v[172:173], v[172:173], 0, s[34:35]
	s_addk_i32 s31, 0xc00
	s_mov_b32 m0, s31
	v_lshl_add_u64 v[168:169], v[172:173], 0, 64
	global_load_lds_dwordx4 v[172:173], off
	s_add_i32 m0, s31, vcc_lo
	s_nop 0
	global_load_lds_dwordx4 v[168:169], off
	v_lshl_add_u64 v[172:173], v[176:177], 0, s[6:7]
	s_add_i32 s9, s9, s27
	s_mov_b32 m0, s9
	v_lshl_add_u64 v[168:169], v[172:173], 0, 64
	global_load_lds_dwordx4 v[172:173], off
	s_add_i32 m0, s9, vcc_lo
	s_nop 0
	global_load_lds_dwordx4 v[168:169], off
	v_lshl_add_u64 v[172:173], v[172:173], 0, s[12:13]
	s_addk_i32 s9, 0x400
	s_mov_b32 m0, s9
	v_lshl_add_u64 v[168:169], v[172:173], 0, 64
	global_load_lds_dwordx4 v[172:173], off
	s_add_i32 m0, s9, vcc_lo
	s_nop 0
	global_load_lds_dwordx4 v[168:169], off
	v_mfma_f32_16x16x32_bf16 v[72:75], v[128:131], v[160:163], v[72:75]
	v_mfma_f32_16x16x32_bf16 v[68:71], v[132:135], v[160:163], v[68:71]
	v_mfma_f32_16x16x32_bf16 v[64:67], v[136:139], v[160:163], v[64:67]
	v_mfma_f32_16x16x32_bf16 v[60:63], v[140:143], v[160:163], v[60:63]
	v_mfma_f32_16x16x32_bf16 v[56:59], v[128:131], v[156:159], v[56:59]
	v_mfma_f32_16x16x32_bf16 v[52:55], v[132:135], v[156:159], v[52:55]
	v_mfma_f32_16x16x32_bf16 v[48:51], v[136:139], v[156:159], v[48:51]
	v_mfma_f32_16x16x32_bf16 v[44:47], v[140:143], v[156:159], v[44:47]
	v_mfma_f32_16x16x32_bf16 v[40:43], v[128:131], v[152:155], v[40:43]
	v_mfma_f32_16x16x32_bf16 v[36:39], v[132:135], v[152:155], v[36:39]
	v_mfma_f32_16x16x32_bf16 v[32:35], v[136:139], v[152:155], v[32:35]
	v_mfma_f32_16x16x32_bf16 v[28:31], v[140:143], v[152:155], v[28:31]
	v_mfma_f32_16x16x32_bf16 v[24:27], v[128:131], v[148:151], v[24:27]
	v_mfma_f32_16x16x32_bf16 v[20:23], v[132:135], v[148:151], v[20:23]
	v_mfma_f32_16x16x32_bf16 v[16:19], v[136:139], v[148:151], v[16:19]
	v_mfma_f32_16x16x32_bf16 v[12:15], v[140:143], v[148:151], v[12:15]
	v_mfma_f32_16x16x32_bf16 v[8:11], v[128:131], v[144:147], v[8:11]
	v_mfma_f32_16x16x32_bf16 v[4:7], v[132:135], v[144:147], v[4:7]
	v_mfma_f32_16x16x32_bf16 v[0:3], v[136:139], v[144:147], v[0:3]
	v_mfma_f32_16x16x32_bf16 v[124:127], v[140:143], v[144:147], v[124:127]
